# v039: v036 + SwiGLU epilogue instruction selection: packed f32 (v_pk_mul/v_pk_add) for g*u, +1.0 and final scale, in-place in acc regs; bit-identical
# speedup vs baseline: 1.0054x; 1.0054x over previous
; __device__ __forceinline__ unsigned cvt_pk_bf16(float lo, float hi) { unsigned r; asm volatile("v_cvt_pk_bf16_f32 %0, %1, %2" : "=v"(r) : "v"(lo), "v"(hi)); return r; }
;     __device__ __forceinline__ void operator()(const f32x4 (&acc)[2][2][4][2], const Unit& u, int wr, int wc, int fr, int fq) const {
;     ...
;         for (int ai = 0; ai < 2; ++ai)
; #pragma unroll
;             for (int m = 0; m < 4; ++m) {
;                 float g8[8], u8[8], v[8];
; #pragma unroll
;                 for (int n = 0; n < 2; ++n)
; #pragma unroll
;                     for (int j = 0; j < 4; ++j) { g8[4 * n + j] = acc[ai][0][m][n][j]; u8[4 * n + j] = acc[ai][1][m][n][j]; }
; #pragma unroll
;                 for (int e = 0; e < 8; ++e) v[e] = __builtin_amdgcn_exp2f(-1.4426950408889634f * g8[e]);
; #pragma unroll
;                 for (int e = 0; e < 8; ++e) v[e] = __builtin_amdgcn_rcpf(1.0f + v[e]);
; #pragma unroll
;                 for (int e = 0; e < 8; ++e) v[e] = (g8[e] * u8[e]) * v[e];
;                 u32x4e w; w.x = cvt_pk_bf16(v[0], v[1]); w.y = cvt_pk_bf16(v[2], v[3]); w.z = cvt_pk_bf16(v[4], v[5]); w.w = cvt_pk_bf16(v[6], v[7]);
;                 *(u32x4e*)(H + (size_t)(row0 + ai * HALF + m * 16) * ldc + col0) = w;
.LBB0_886:
	v_pk_mul_f32 v[116:117], v[124:125], v[116:117]
	v_pk_mul_f32 v[118:119], v[126:127], v[118:119]
	v_pk_mul_f32 v[120:121], v[128:129], v[120:121]
	v_pk_mul_f32 v[122:123], v[130:131], v[122:123]
	v_mul_f32_e32 v124, 0xbfb8aa3b, v124
	v_mul_f32_e32 v125, 0xbfb8aa3b, v125
	v_mul_f32_e32 v126, 0xbfb8aa3b, v126
	v_mul_f32_e32 v127, 0xbfb8aa3b, v127
	v_mul_f32_e32 v128, 0xbfb8aa3b, v128
	v_mul_f32_e32 v129, 0xbfb8aa3b, v129
	v_mul_f32_e32 v130, 0xbfb8aa3b, v130
	v_mul_f32_e32 v131, 0xbfb8aa3b, v131
	v_exp_f32_e32 v124, v124
	v_exp_f32_e32 v125, v125
	v_exp_f32_e32 v126, v126
	v_exp_f32_e32 v127, v127
	v_exp_f32_e32 v128, v128
	v_exp_f32_e32 v129, v129
	v_exp_f32_e32 v130, v130
	v_exp_f32_e32 v131, v131
	s_nop 0
	v_pk_add_f32 v[124:125], v[124:125], 1.0 op_sel_hi:[1,0]
	v_pk_add_f32 v[126:127], v[126:127], 1.0 op_sel_hi:[1,0]
	v_pk_add_f32 v[128:129], v[128:129], 1.0 op_sel_hi:[1,0]
	v_pk_add_f32 v[130:131], v[130:131], 1.0 op_sel_hi:[1,0]
	v_rcp_f32_e32 v124, v124
	v_rcp_f32_e32 v125, v125
	v_rcp_f32_e32 v126, v126
	v_rcp_f32_e32 v127, v127
	v_rcp_f32_e32 v128, v128
	v_rcp_f32_e32 v129, v129
	v_rcp_f32_e32 v130, v130
	v_rcp_f32_e32 v131, v131
	s_nop 0
	v_pk_mul_f32 v[116:117], v[124:125], v[116:117]
	v_pk_mul_f32 v[118:119], v[126:127], v[118:119]
	v_pk_mul_f32 v[120:121], v[128:129], v[120:121]
	v_pk_mul_f32 v[122:123], v[130:131], v[122:123]
	v_lshl_or_b32 v144, s30, 7, v142
	v_lshl_add_u32 v146, s31, 8, v140
	v_ashrrev_i32_e32 v145, 31, v144
	v_cvt_pk_bf16_f32 v120, v120, v121
	v_cvt_pk_bf16_f32 v121, v122, v123
	v_cvt_pk_bf16_f32 v122, v116, v117
	v_mov_b64_e32 v[116:117], s[50:51]
	v_cvt_pk_bf16_f32 v123, v118, v119
	v_mad_i64_i32 v[124:125], s[16:17], v146, s44, v[116:117]
	v_lshlrev_b64 v[118:119], 1, v[144:145]
	v_lshl_add_u64 v[124:125], v[124:125], 0, v[118:119]
	global_store_dwordx4 v[124:125], v[120:123], off sc1
	v_pk_mul_f32 v[100:101], v[108:109], v[100:101]
	v_pk_mul_f32 v[102:103], v[110:111], v[102:103]
	v_pk_mul_f32 v[104:105], v[112:113], v[104:105]
	v_pk_mul_f32 v[106:107], v[114:115], v[106:107]
	v_mul_f32_e32 v108, 0xbfb8aa3b, v108
	v_mul_f32_e32 v109, 0xbfb8aa3b, v109
	v_mul_f32_e32 v110, 0xbfb8aa3b, v110
	v_mul_f32_e32 v111, 0xbfb8aa3b, v111
	v_mul_f32_e32 v112, 0xbfb8aa3b, v112
	v_mul_f32_e32 v113, 0xbfb8aa3b, v113
	v_mul_f32_e32 v114, 0xbfb8aa3b, v114
	v_mul_f32_e32 v115, 0xbfb8aa3b, v115
	v_exp_f32_e32 v108, v108
	v_exp_f32_e32 v109, v109
	v_exp_f32_e32 v110, v110
	v_exp_f32_e32 v111, v111
	v_exp_f32_e32 v112, v112
	v_exp_f32_e32 v113, v113
	v_exp_f32_e32 v114, v114
	v_exp_f32_e32 v115, v115
	s_nop 0
	v_pk_add_f32 v[108:109], v[108:109], 1.0 op_sel_hi:[1,0]
	v_pk_add_f32 v[110:111], v[110:111], 1.0 op_sel_hi:[1,0]
	v_pk_add_f32 v[112:113], v[112:113], 1.0 op_sel_hi:[1,0]
	v_pk_add_f32 v[114:115], v[114:115], 1.0 op_sel_hi:[1,0]
	v_rcp_f32_e32 v108, v108
	v_rcp_f32_e32 v109, v109
	v_rcp_f32_e32 v110, v110
	v_rcp_f32_e32 v111, v111
	v_rcp_f32_e32 v112, v112
	v_rcp_f32_e32 v113, v113
	v_rcp_f32_e32 v114, v114
	v_rcp_f32_e32 v115, v115
	s_nop 0
	v_pk_mul_f32 v[108:109], v[108:109], v[100:101]
	v_mul_f32_e32 v110, v110, v102
	v_mul_f32_e32 v103, v111, v103
	v_pk_mul_f32 v[104:105], v[112:113], v[104:105]
	v_pk_mul_f32 v[106:107], v[114:115], v[106:107]
	v_cvt_pk_bf16_f32 v100, v104, v105
	v_or_b32_e32 v104, 16, v146
	v_mad_i64_i32 v[104:105], s[16:17], v104, s44, v[116:117]
	v_lshl_add_u64 v[104:105], v[104:105], 0, v[118:119]
	v_cvt_pk_bf16_f32 v101, v106, v107
	v_cvt_pk_bf16_f32 v102, v108, v109
	v_cvt_pk_bf16_f32 v103, v110, v103
	global_store_dwordx4 v[104:105], v[100:103], off sc1
	v_pk_mul_f32 v[84:85], v[92:93], v[84:85]
	v_pk_mul_f32 v[86:87], v[94:95], v[86:87]
	v_pk_mul_f32 v[88:89], v[96:97], v[88:89]
	v_pk_mul_f32 v[90:91], v[98:99], v[90:91]
	v_mul_f32_e32 v92, 0xbfb8aa3b, v92
	v_mul_f32_e32 v93, 0xbfb8aa3b, v93
	v_mul_f32_e32 v94, 0xbfb8aa3b, v94
	v_mul_f32_e32 v95, 0xbfb8aa3b, v95
	v_mul_f32_e32 v96, 0xbfb8aa3b, v96
	v_mul_f32_e32 v97, 0xbfb8aa3b, v97
	v_mul_f32_e32 v98, 0xbfb8aa3b, v98
	v_mul_f32_e32 v99, 0xbfb8aa3b, v99
	v_exp_f32_e32 v92, v92
	v_exp_f32_e32 v93, v93
	v_exp_f32_e32 v94, v94
	v_exp_f32_e32 v95, v95
	v_exp_f32_e32 v96, v96
	v_exp_f32_e32 v97, v97
	v_exp_f32_e32 v98, v98
	v_exp_f32_e32 v99, v99
	s_nop 0
	v_pk_add_f32 v[92:93], v[92:93], 1.0 op_sel_hi:[1,0]
	v_pk_add_f32 v[94:95], v[94:95], 1.0 op_sel_hi:[1,0]
	v_pk_add_f32 v[96:97], v[96:97], 1.0 op_sel_hi:[1,0]
	v_pk_add_f32 v[98:99], v[98:99], 1.0 op_sel_hi:[1,0]
	v_rcp_f32_e32 v92, v92
	v_rcp_f32_e32 v93, v93
	v_rcp_f32_e32 v94, v94
	v_rcp_f32_e32 v95, v95
	v_rcp_f32_e32 v96, v96
	v_rcp_f32_e32 v97, v97
	v_rcp_f32_e32 v98, v98
	v_rcp_f32_e32 v99, v99
	s_nop 0
	v_pk_mul_f32 v[92:93], v[92:93], v[84:85]
	v_mul_f32_e32 v94, v94, v86
	v_mul_f32_e32 v87, v95, v87
	v_pk_mul_f32 v[88:89], v[96:97], v[88:89]
	v_pk_mul_f32 v[90:91], v[98:99], v[90:91]
	v_cvt_pk_bf16_f32 v84, v88, v89
	v_or_b32_e32 v88, 32, v146
	v_mad_i64_i32 v[88:89], s[16:17], v88, s44, v[116:117]
	v_lshl_add_u64 v[88:89], v[88:89], 0, v[118:119]
	v_cvt_pk_bf16_f32 v85, v90, v91
	v_cvt_pk_bf16_f32 v86, v92, v93
	v_cvt_pk_bf16_f32 v87, v94, v87
	global_store_dwordx4 v[88:89], v[84:87], off sc1
	v_pk_mul_f32 v[68:69], v[76:77], v[68:69]
	v_pk_mul_f32 v[70:71], v[78:79], v[70:71]
	v_pk_mul_f32 v[72:73], v[80:81], v[72:73]
	v_pk_mul_f32 v[74:75], v[82:83], v[74:75]
	v_mul_f32_e32 v76, 0xbfb8aa3b, v76
	v_mul_f32_e32 v77, 0xbfb8aa3b, v77
	v_mul_f32_e32 v78, 0xbfb8aa3b, v78
	v_mul_f32_e32 v79, 0xbfb8aa3b, v79
	v_mul_f32_e32 v80, 0xbfb8aa3b, v80
	v_mul_f32_e32 v81, 0xbfb8aa3b, v81
	v_mul_f32_e32 v82, 0xbfb8aa3b, v82
	v_mul_f32_e32 v83, 0xbfb8aa3b, v83
	v_exp_f32_e32 v76, v76
; __device__ __forceinline__ unsigned cvt_pk_bf16(float lo, float hi) { unsigned r; asm volatile("v_cvt_pk_bf16_f32 %0, %1, %2" : "=v"(r) : "v"(lo), "v"(hi)); return r; }
;     __device__ __forceinline__ void operator()(const f32x4 (&acc)[2][2][4][2], const Unit& u, int wr, int wc, int fr, int fq) const {
;     ...
;         for (int ai = 0; ai < 2; ++ai)
; #pragma unroll
;             for (int m = 0; m < 4; ++m) {
;                 float g8[8], u8[8], v[8];
; #pragma unroll
;                 for (int n = 0; n < 2; ++n)
; #pragma unroll
;                     for (int j = 0; j < 4; ++j) { g8[4 * n + j] = acc[ai][0][m][n][j]; u8[4 * n + j] = acc[ai][1][m][n][j]; }
; #pragma unroll
;                 for (int e = 0; e < 8; ++e) v[e] = __builtin_amdgcn_exp2f(-1.4426950408889634f * g8[e]);
; #pragma unroll
;                 for (int e = 0; e < 8; ++e) v[e] = __builtin_amdgcn_rcpf(1.0f + v[e]);
; #pragma unroll
;                 for (int e = 0; e < 8; ++e) v[e] = (g8[e] * u8[e]) * v[e];
;                 u32x4e w; w.x = cvt_pk_bf16(v[0], v[1]); w.y = cvt_pk_bf16(v[2], v[3]); w.z = cvt_pk_bf16(v[4], v[5]); w.w = cvt_pk_bf16(v[6], v[7]);
;                 *(u32x4e*)(H + (size_t)(row0 + ai * HALF + m * 16) * ldc + col0) = w;
	v_exp_f32_e32 v77, v77
	v_exp_f32_e32 v78, v78
	v_exp_f32_e32 v79, v79
	v_exp_f32_e32 v80, v80
	v_exp_f32_e32 v81, v81
	v_exp_f32_e32 v82, v82
	v_exp_f32_e32 v83, v83
	s_nop 0
	v_pk_add_f32 v[76:77], v[76:77], 1.0 op_sel_hi:[1,0]
	v_pk_add_f32 v[78:79], v[78:79], 1.0 op_sel_hi:[1,0]
	v_pk_add_f32 v[80:81], v[80:81], 1.0 op_sel_hi:[1,0]
	v_pk_add_f32 v[82:83], v[82:83], 1.0 op_sel_hi:[1,0]
	v_rcp_f32_e32 v76, v76
	v_rcp_f32_e32 v77, v77
	v_rcp_f32_e32 v78, v78
	v_rcp_f32_e32 v79, v79
	v_rcp_f32_e32 v80, v80
	v_rcp_f32_e32 v81, v81
	v_rcp_f32_e32 v82, v82
	v_rcp_f32_e32 v83, v83
	s_nop 0
	v_pk_mul_f32 v[76:77], v[76:77], v[68:69]
	v_mul_f32_e32 v78, v78, v70
	v_mul_f32_e32 v71, v79, v71
	v_pk_mul_f32 v[72:73], v[80:81], v[72:73]
	v_pk_mul_f32 v[74:75], v[82:83], v[74:75]
	v_cvt_pk_bf16_f32 v68, v72, v73
	v_or_b32_e32 v72, 48, v146
	v_mad_i64_i32 v[72:73], s[16:17], v72, s44, v[116:117]
	v_lshl_add_u64 v[72:73], v[72:73], 0, v[118:119]
	v_cvt_pk_bf16_f32 v69, v74, v75
	v_cvt_pk_bf16_f32 v70, v76, v77
	v_cvt_pk_bf16_f32 v71, v78, v71
	global_store_dwordx4 v[72:73], v[68:71], off sc1
	v_pk_mul_f32 v[52:53], v[60:61], v[52:53]
	v_pk_mul_f32 v[54:55], v[62:63], v[54:55]
	v_pk_mul_f32 v[56:57], v[64:65], v[56:57]
	v_pk_mul_f32 v[58:59], v[66:67], v[58:59]
	v_mul_f32_e32 v60, 0xbfb8aa3b, v60
	v_mul_f32_e32 v61, 0xbfb8aa3b, v61
	v_mul_f32_e32 v62, 0xbfb8aa3b, v62
	v_mul_f32_e32 v63, 0xbfb8aa3b, v63
	v_mul_f32_e32 v64, 0xbfb8aa3b, v64
	v_mul_f32_e32 v65, 0xbfb8aa3b, v65
	v_mul_f32_e32 v66, 0xbfb8aa3b, v66
	v_mul_f32_e32 v67, 0xbfb8aa3b, v67
	v_exp_f32_e32 v60, v60
	v_exp_f32_e32 v61, v61
	v_exp_f32_e32 v62, v62
	v_exp_f32_e32 v63, v63
	v_exp_f32_e32 v64, v64
	v_exp_f32_e32 v65, v65
	v_exp_f32_e32 v66, v66
	v_exp_f32_e32 v67, v67
	s_nop 0
	v_pk_add_f32 v[60:61], v[60:61], 1.0 op_sel_hi:[1,0]
	v_pk_add_f32 v[62:63], v[62:63], 1.0 op_sel_hi:[1,0]
	v_pk_add_f32 v[64:65], v[64:65], 1.0 op_sel_hi:[1,0]
	v_pk_add_f32 v[66:67], v[66:67], 1.0 op_sel_hi:[1,0]
	v_rcp_f32_e32 v60, v60
	v_rcp_f32_e32 v61, v61
	v_rcp_f32_e32 v62, v62
	v_rcp_f32_e32 v63, v63
	v_rcp_f32_e32 v64, v64
	v_rcp_f32_e32 v65, v65
	v_rcp_f32_e32 v66, v66
	v_rcp_f32_e32 v67, v67
	s_nop 0
	v_pk_mul_f32 v[60:61], v[60:61], v[52:53]
	v_mul_f32_e32 v62, v62, v54
	v_mul_f32_e32 v55, v63, v55
	v_pk_mul_f32 v[56:57], v[64:65], v[56:57]
	v_pk_mul_f32 v[58:59], v[66:67], v[58:59]
	v_add_u32_e32 v68, 0x80, v146
	v_cvt_pk_bf16_f32 v52, v56, v57
	v_mad_i64_i32 v[56:57], s[16:17], v68, s44, v[116:117]
	v_lshl_add_u64 v[56:57], v[56:57], 0, v[118:119]
	v_cvt_pk_bf16_f32 v53, v58, v59
	v_cvt_pk_bf16_f32 v54, v60, v61
	v_cvt_pk_bf16_f32 v55, v62, v55
	global_store_dwordx4 v[56:57], v[52:55], off sc1
	v_pk_mul_f32 v[36:37], v[44:45], v[36:37]
	v_pk_mul_f32 v[38:39], v[46:47], v[38:39]
	v_pk_mul_f32 v[40:41], v[48:49], v[40:41]
	v_pk_mul_f32 v[42:43], v[50:51], v[42:43]
	v_mul_f32_e32 v44, 0xbfb8aa3b, v44
	v_mul_f32_e32 v45, 0xbfb8aa3b, v45
	v_mul_f32_e32 v46, 0xbfb8aa3b, v46
	v_mul_f32_e32 v47, 0xbfb8aa3b, v47
	v_mul_f32_e32 v48, 0xbfb8aa3b, v48
	v_mul_f32_e32 v49, 0xbfb8aa3b, v49
	v_mul_f32_e32 v50, 0xbfb8aa3b, v50
	v_mul_f32_e32 v51, 0xbfb8aa3b, v51
	v_exp_f32_e32 v44, v44
	v_exp_f32_e32 v45, v45
	v_exp_f32_e32 v46, v46
	v_exp_f32_e32 v47, v47
	v_exp_f32_e32 v48, v48
	v_exp_f32_e32 v49, v49
	v_exp_f32_e32 v50, v50
	v_exp_f32_e32 v51, v51
	s_nop 0
	v_pk_add_f32 v[44:45], v[44:45], 1.0 op_sel_hi:[1,0]
	v_pk_add_f32 v[46:47], v[46:47], 1.0 op_sel_hi:[1,0]
	v_pk_add_f32 v[48:49], v[48:49], 1.0 op_sel_hi:[1,0]
	v_pk_add_f32 v[50:51], v[50:51], 1.0 op_sel_hi:[1,0]
	v_rcp_f32_e32 v44, v44
	v_rcp_f32_e32 v45, v45
	v_rcp_f32_e32 v46, v46
	v_rcp_f32_e32 v47, v47
	v_rcp_f32_e32 v48, v48
	v_rcp_f32_e32 v49, v49
	v_rcp_f32_e32 v50, v50
	v_rcp_f32_e32 v51, v51
	s_nop 0
	v_pk_mul_f32 v[44:45], v[44:45], v[36:37]
; __device__ __forceinline__ unsigned cvt_pk_bf16(float lo, float hi) { unsigned r; asm volatile("v_cvt_pk_bf16_f32 %0, %1, %2" : "=v"(r) : "v"(lo), "v"(hi)); return r; }
;     __device__ __forceinline__ void operator()(const f32x4 (&acc)[2][2][4][2], const Unit& u, int wr, int wc, int fr, int fq) const {
;     ...
;         for (int ai = 0; ai < 2; ++ai)
; #pragma unroll
;             for (int m = 0; m < 4; ++m) {
;                 float g8[8], u8[8], v[8];
; #pragma unroll
;                 for (int n = 0; n < 2; ++n)
; #pragma unroll
;                     for (int j = 0; j < 4; ++j) { g8[4 * n + j] = acc[ai][0][m][n][j]; u8[4 * n + j] = acc[ai][1][m][n][j]; }
; #pragma unroll
;                 for (int e = 0; e < 8; ++e) v[e] = __builtin_amdgcn_exp2f(-1.4426950408889634f * g8[e]);
; #pragma unroll
;                 for (int e = 0; e < 8; ++e) v[e] = __builtin_amdgcn_rcpf(1.0f + v[e]);
; #pragma unroll
;                 for (int e = 0; e < 8; ++e) v[e] = (g8[e] * u8[e]) * v[e];
;                 u32x4e w; w.x = cvt_pk_bf16(v[0], v[1]); w.y = cvt_pk_bf16(v[2], v[3]); w.z = cvt_pk_bf16(v[4], v[5]); w.w = cvt_pk_bf16(v[6], v[7]);
;                 *(u32x4e*)(H + (size_t)(row0 + ai * HALF + m * 16) * ldc + col0) = w;
	v_mul_f32_e32 v46, v46, v38
	v_mul_f32_e32 v39, v47, v39
	v_pk_mul_f32 v[40:41], v[48:49], v[40:41]
	v_pk_mul_f32 v[42:43], v[50:51], v[42:43]
	v_cvt_pk_bf16_f32 v36, v40, v41
	v_add_u32_e32 v40, 0x90, v146
	v_mad_i64_i32 v[40:41], s[16:17], v40, s44, v[116:117]
	v_lshl_add_u64 v[40:41], v[40:41], 0, v[118:119]
	v_cvt_pk_bf16_f32 v37, v42, v43
	v_cvt_pk_bf16_f32 v38, v44, v45
	v_cvt_pk_bf16_f32 v39, v46, v39
	global_store_dwordx4 v[40:41], v[36:39], off sc1
	v_pk_mul_f32 v[20:21], v[28:29], v[20:21]
	v_pk_mul_f32 v[22:23], v[30:31], v[22:23]
	v_pk_mul_f32 v[24:25], v[32:33], v[24:25]
	v_pk_mul_f32 v[26:27], v[34:35], v[26:27]
	v_mul_f32_e32 v28, 0xbfb8aa3b, v28
	v_mul_f32_e32 v29, 0xbfb8aa3b, v29
	v_mul_f32_e32 v30, 0xbfb8aa3b, v30
	v_mul_f32_e32 v31, 0xbfb8aa3b, v31
	v_mul_f32_e32 v32, 0xbfb8aa3b, v32
	v_mul_f32_e32 v33, 0xbfb8aa3b, v33
	v_mul_f32_e32 v34, 0xbfb8aa3b, v34
	v_mul_f32_e32 v35, 0xbfb8aa3b, v35
	v_exp_f32_e32 v28, v28
	v_exp_f32_e32 v29, v29
	v_exp_f32_e32 v30, v30
	v_exp_f32_e32 v31, v31
	v_exp_f32_e32 v32, v32
	v_exp_f32_e32 v33, v33
	v_exp_f32_e32 v34, v34
	v_exp_f32_e32 v35, v35
	s_nop 0
	v_pk_add_f32 v[28:29], v[28:29], 1.0 op_sel_hi:[1,0]
	v_pk_add_f32 v[30:31], v[30:31], 1.0 op_sel_hi:[1,0]
	v_pk_add_f32 v[32:33], v[32:33], 1.0 op_sel_hi:[1,0]
	v_pk_add_f32 v[34:35], v[34:35], 1.0 op_sel_hi:[1,0]
	v_rcp_f32_e32 v28, v28
	v_rcp_f32_e32 v29, v29
	v_rcp_f32_e32 v30, v30
	v_rcp_f32_e32 v31, v31
	v_rcp_f32_e32 v32, v32
	v_rcp_f32_e32 v33, v33
	v_rcp_f32_e32 v34, v34
	v_rcp_f32_e32 v35, v35
	s_nop 0
	v_pk_mul_f32 v[28:29], v[28:29], v[20:21]
	v_mul_f32_e32 v30, v30, v22
	v_mul_f32_e32 v23, v31, v23
	v_pk_mul_f32 v[24:25], v[32:33], v[24:25]
	v_pk_mul_f32 v[26:27], v[34:35], v[26:27]
	v_cvt_pk_bf16_f32 v20, v24, v25
	v_add_u32_e32 v24, 0xa0, v146
	v_mad_i64_i32 v[24:25], s[16:17], v24, s44, v[116:117]
	v_lshl_add_u64 v[24:25], v[24:25], 0, v[118:119]
	v_cvt_pk_bf16_f32 v21, v26, v27
	v_cvt_pk_bf16_f32 v22, v28, v29
	v_cvt_pk_bf16_f32 v23, v30, v23
	global_store_dwordx4 v[24:25], v[20:23], off sc1
	v_pk_mul_f32 v[4:5], v[12:13], v[4:5]
	v_pk_mul_f32 v[6:7], v[14:15], v[6:7]
	v_pk_mul_f32 v[8:9], v[16:17], v[8:9]
	v_pk_mul_f32 v[10:11], v[18:19], v[10:11]
	v_mul_f32_e32 v12, 0xbfb8aa3b, v12
	v_mul_f32_e32 v13, 0xbfb8aa3b, v13
	v_mul_f32_e32 v14, 0xbfb8aa3b, v14
	v_mul_f32_e32 v15, 0xbfb8aa3b, v15
	v_mul_f32_e32 v16, 0xbfb8aa3b, v16
	v_mul_f32_e32 v17, 0xbfb8aa3b, v17
	v_mul_f32_e32 v18, 0xbfb8aa3b, v18
	v_mul_f32_e32 v19, 0xbfb8aa3b, v19
	v_exp_f32_e32 v12, v12
	v_exp_f32_e32 v13, v13
	v_exp_f32_e32 v14, v14
	v_exp_f32_e32 v15, v15
	v_exp_f32_e32 v16, v16
	v_exp_f32_e32 v17, v17
	v_exp_f32_e32 v18, v18
	v_exp_f32_e32 v19, v19
	s_nop 0
	v_pk_add_f32 v[12:13], v[12:13], 1.0 op_sel_hi:[1,0]
	v_pk_add_f32 v[14:15], v[14:15], 1.0 op_sel_hi:[1,0]
	v_pk_add_f32 v[16:17], v[16:17], 1.0 op_sel_hi:[1,0]
	v_pk_add_f32 v[18:19], v[18:19], 1.0 op_sel_hi:[1,0]
	v_rcp_f32_e32 v12, v12
	v_rcp_f32_e32 v13, v13
	v_rcp_f32_e32 v14, v14
	v_rcp_f32_e32 v15, v15
	v_rcp_f32_e32 v16, v16
	v_rcp_f32_e32 v17, v17
	v_rcp_f32_e32 v18, v18
	v_rcp_f32_e32 v19, v19
	s_nop 0
	v_pk_mul_f32 v[12:13], v[12:13], v[4:5]
	v_mul_f32_e32 v14, v14, v6
	v_mul_f32_e32 v7, v15, v7
	v_pk_mul_f32 v[8:9], v[16:17], v[8:9]
	v_pk_mul_f32 v[10:11], v[18:19], v[10:11]
	v_cvt_pk_bf16_f32 v4, v8, v9
	v_add_u32_e32 v8, 0xb0, v146
	v_mad_i64_i32 v[8:9], s[16:17], v8, s44, v[116:117]
	v_lshl_add_u64 v[8:9], v[8:9], 0, v[118:119]
	s_andn2_b64 vcc, exec, s[0:1]
	s_mov_b64 s[0:1], -1
	v_cvt_pk_bf16_f32 v5, v10, v11
	v_cvt_pk_bf16_f32 v6, v12, v13
	v_cvt_pk_bf16_f32 v7, v14, v7
	global_store_dwordx4 v[8:9], v[4:7], off sc1
	s_cbranch_vccnz .LBB0_879
	s_andn2_b64 vcc, exec, s[4:5]
	s_cbranch_vccnz .LBB0_878
	s_barrier
	s_branch .LBB0_878
